# bias staging loads batched; redundant L1 invalidates removed at LN-stats poll and split-phase waits
# speedup vs baseline: 1.0046x; 1.0046x over previous
; #define LAS __attribute__((address_space(3)))
; __device__ __forceinline__ int otid(int wave) { return wave * 64 + olane(); }
; __device__ __forceinline__ unsigned xb_ld(unsigned* p)              { return __hip_atomic_load(p, __ATOMIC_RELAXED, __HIP_MEMORY_SCOPE_AGENT); }
; #define XB_SPIN(cond, bar) do { unsigned _sp = 0; while (cond) { __builtin_amdgcn_s_sleep(1); \
;     if ((++_sp & 255u) == 0u) { if (xb_ld(&(bar)[XB_TMO])) break; if (_sp > XB_SPIN_CAP) { atomicAdd(&(bar)[XB_TMO], 1u); break; } } } } while (0)
; __device__ __forceinline__ bool is_t0(int wave) { return wave == 0 && olane() == 0; }
; __device__ __forceinline__ void xcdl_wait_t0(const XcdBarrier& b) {
;     if (is_t0(b.wave)) {
;         unsigned* bar = b.bar; asm volatile("" : "+s"(bar));
;         const unsigned gen = b.st[5];
;         XB_SPIN(xb_ld(&bar[XB_LGEN(b.x)]) == gen, bar);
;         __builtin_amdgcn_fence(__ATOMIC_ACQUIRE, "agent");
;         asm volatile("s_waitcnt vmcnt(0)" ::: "memory");
; __global__ void __launch_bounds__(512, 2) mk_fwd(Args args) {
;     ...
;                 LAS float* lb = (LAS float*)(F.lds + 131072); P.lbias = lb; const int t_ = otid(F.wave);
; #pragma unroll
;                 for (int i = 0; i < 4; ++i) { const int e = i * 512 + t_, slot = e >> 8; const int pn_ = (P1_MAP == 1) ? (((cid >> 3) & 7) + 8 * (slot & 3)) : (4 * slot + (cid >> 6)); lb[e] = P.biasp[256 * pn_ + (e & 255)]; }
;                 if (splitb && (SPLIT_BAR & 2) && L > 0) xcdl_wait_t0(bar);
;                 if (psync && (PSYNC & 2) && L > 0) psync_wait((unsigned*)(ctl + CW_PSYNC + (2 * (L - 1) + 1) * 1024 + 16 * (8 * (cid & 7) + ((cid >> 3) & 7))), (unsigned*)(ctl + CW_TMO), 0x910u);
;                 __syncthreads(); }
.LBB0_174:
	s_lshl_b32 s34, s58, 2
	s_or_b32 s2, s34, 1
	s_cmp_le_i32 s66, s2
	s_cselect_b64 s[0:1], -1, 0
	s_cmp_lt_i32 s2, s67
	s_cselect_b64 s[2:3], -1, 0
	v_writelane_b32 v254, s60, 52
	s_and_b64 s[2:3], s[0:1], s[2:3]
	s_andn2_b64 vcc, exec, s[2:3]
	v_writelane_b32 v254, s61, 53
	v_writelane_b32 v254, s34, 54
	s_cbranch_vccnz .LBB0_398
	v_readlane_b32 s0, v254, 11
	s_mov_b64 s[42:43], s[82:83]
	v_readlane_b32 s1, v254, 12
	s_lshl_b32 s78, s58, 13
	v_mbcnt_lo_u32_b32 v0, -1, 0
	v_mbcnt_hi_u32_b32 v0, -1, v0
	s_and_b64 s[0:1], s[88:89], s[0:1]
	v_add_u32_e32 v2, s70, v0
	s_lshl_b64 s[6:7], s[78:79], 2
	v_lshrrev_b32_e32 v0, 6, v2
	s_add_u32 s6, s42, s6
	v_and_b32_e32 v0, 0xfffffc, v0
	v_readlane_b32 s8, v253, 7
	s_addc_u32 s7, s43, s7
	v_and_b32_e32 v3, 0xff, v2
	v_add_u32_e32 v0, s8, v0
	s_add_u32 s6, s6, 0x1d80000
	v_lshl_or_b32 v0, v0, 8, v3
	s_addc_u32 s7, s7, 0
	v_ashrrev_i32_e32 v1, 31, v0
	v_lshl_add_u64 v[0:1], v[0:1], 2, s[6:7]
	flat_load_dword v4, v[0:1]
	v_lshl_add_u32 v0, v2, 2, 0
	v_add_u32_e32 v1, 0x200, v2
	v_add_u32_e32 v5, 0x20000, v0
	v_lshrrev_b32_e32 v0, 6, v1
	v_and_b32_e32 v0, 0xfffffc, v0
	v_add_u32_e32 v0, s8, v0
	v_lshl_or_b32 v0, v0, 8, v3
	v_ashrrev_i32_e32 v1, 31, v0
	v_lshl_add_u64 v[0:1], v[0:1], 2, s[6:7]
	s_andn2_b64 vcc, exec, s[0:1]
	flat_load_dword v6, v[0:1]
	v_add_u32_e32 v0, 0x400, v2
	v_lshrrev_b32_e32 v0, 6, v0
	v_and_b32_e32 v0, 0xfffffc, v0
	v_add_u32_e32 v0, s8, v0
	v_lshl_or_b32 v0, v0, 8, v3
	v_ashrrev_i32_e32 v1, 31, v0
	v_lshl_add_u64 v[0:1], v[0:1], 2, s[6:7]
	flat_load_dword v7, v[0:1]
	v_add_u32_e32 v0, 0x600, v2
	v_lshrrev_b32_e32 v0, 6, v0
	v_and_b32_e32 v0, 0xfffffc, v0
	v_add_u32_e32 v0, s8, v0
	v_lshl_or_b32 v0, v0, 8, v3
	v_ashrrev_i32_e32 v1, 31, v0
	v_lshl_add_u64 v[0:1], v[0:1], 2, s[6:7]
	flat_load_dword v8, v[0:1]
	s_nop 0
	s_nop 0
	s_nop 0
	s_waitcnt vmcnt(0) lgkmcnt(0)
	ds_write_b32 v5, v4
	ds_write_b32 v5, v6 offset:2048
	ds_write_b32 v5, v7 offset:4096
	ds_write_b32 v5, v8 offset:6144
	s_cbranch_vccnz .LBB0_190
	v_mbcnt_lo_u32_b32 v0, -1, 0
	v_mbcnt_hi_u32_b32 v0, -1, v0
	s_nop 0
	v_cmp_eq_u32_e32 vcc, 0, v0
	s_and_saveexec_b64 s[6:7], vcc
	s_cbranch_execz .LBB0_189
	s_mov_b64 s[28:29], s[26:27]
	s_lshl_b32 s0, s23, 2
	s_add_u32 s0, s28, s0
	s_addc_u32 s1, s29, 0
	v_mov_b32_e32 v1, s0
	v_add_co_u32_e32 v2, vcc, 0x4000, v1
	v_mov_b32_e32 v1, s1
	v_mov_b32_e32 v0, s21
	v_addc_co_u32_e32 v3, vcc, 0, v1, vcc
	ds_read_b32 v0, v0
	flat_load_dword v1, v[2:3] offset:1536 sc1
	s_add_u32 s38, s0, 0x4600
	s_addc_u32 s39, s1, 0
	s_waitcnt vmcnt(0) lgkmcnt(0)
	v_cmp_eq_u32_e32 vcc, v1, v0
	s_and_saveexec_b64 s[30:31], vcc
	s_cbranch_execz .LBB0_188
	s_mov_b32 s16, 1
	s_mov_b64 s[8:9], 0
	s_branch .LBB0_180

; __device__ __forceinline__ unsigned xb_ld(unsigned* p)              { return __hip_atomic_load(p, __ATOMIC_RELAXED, __HIP_MEMORY_SCOPE_AGENT); }
; #define XB_SPIN(cond, bar) do { unsigned _sp = 0; while (cond) { __builtin_amdgcn_s_sleep(1); \
;     if ((++_sp & 255u) == 0u) { if (xb_ld(&(bar)[XB_TMO])) break; if (_sp > XB_SPIN_CAP) { atomicAdd(&(bar)[XB_TMO], 1u); break; } } } } while (0)
; __device__ __forceinline__ bool is_t0(int wave) { return wave == 0 && olane() == 0; }
; __device__ __forceinline__ void xcdl_wait_t0(const XcdBarrier& b) {
;     if (is_t0(b.wave)) {
;         unsigned* bar = b.bar; asm volatile("" : "+s"(bar));
;         const unsigned gen = b.st[5];
;         XB_SPIN(xb_ld(&bar[XB_LGEN(b.x)]) == gen, bar);
;         __builtin_amdgcn_fence(__ATOMIC_ACQUIRE, "agent");
;         asm volatile("s_waitcnt vmcnt(0)" ::: "memory");
;     }
.LBB0_188:
	s_or_b64 exec, exec, s[30:31]
	s_waitcnt vmcnt(0) lgkmcnt(0)
	s_nop 0
	s_nop 0
	s_waitcnt vmcnt(0)

; __device__ __forceinline__ unsigned xb_ld(unsigned* p)              { return __hip_atomic_load(p, __ATOMIC_RELAXED, __HIP_MEMORY_SCOPE_AGENT); }
; #define XB_SPIN(cond, bar) do { unsigned _sp = 0; while (cond) { __builtin_amdgcn_s_sleep(1); \
;     if ((++_sp & 255u) == 0u) { if (xb_ld(&(bar)[XB_TMO])) break; if (_sp > XB_SPIN_CAP) { atomicAdd(&(bar)[XB_TMO], 1u); break; } } } } while (0)
; __device__ __forceinline__ bool is_t0(int wave) { return wave == 0 && olane() == 0; }
; __device__ __forceinline__ void xcdl_wait_t0(const XcdBarrier& b) {
;     if (is_t0(b.wave)) {
;         unsigned* bar = b.bar; asm volatile("" : "+s"(bar));
;         const unsigned gen = b.st[5];
;         XB_SPIN(xb_ld(&bar[XB_LGEN(b.x)]) == gen, bar);
;         __builtin_amdgcn_fence(__ATOMIC_ACQUIRE, "agent");
;         asm volatile("s_waitcnt vmcnt(0)" ::: "memory");
;     }
;     __device__ __forceinline__ void gate() const {
;         if (gate_cnt) psync_wait(gate_cnt, st.tmo, 0x900u);
;         if (gate_xcc) { xcdl_wait_t0(gb); asm volatile("s_waitcnt lgkmcnt(0)" ::: "memory"); __builtin_amdgcn_s_barrier(); asm volatile("" ::: "memory"); }
;     }
.LBB0_761:
	s_or_b64 exec, exec, s[38:39]
	s_waitcnt vmcnt(0) lgkmcnt(0)
	s_nop 0
	s_nop 0
	s_waitcnt vmcnt(0)

;     __device__ __forceinline__ bool run(const Acc& v, int pm, int pn, int wr, int wc, int fr, int fq, LAS unsigned char* lds, int wid, int lane) const {
;     ...
;         if (wid == 0) {
;             bool dead = false; const unsigned long long t0 = __builtin_amdgcn_s_memrealtime(); const unsigned want = 32u;
;             for (;;) {
;                 if ((unsigned)__builtin_amdgcn_readfirstlane(__hip_atomic_load(cnt + 64 * pm, __ATOMIC_RELAXED, __HIP_MEMORY_SCOPE_AGENT)) >= want) break;
;                 if (__builtin_amdgcn_s_memrealtime() - t0 > 2000000ull) {
;                     if (lane == 0) { unsigned expect = 0u; __hip_atomic_compare_exchange_strong(tmo + 1, &expect, code | (unsigned)(pm & 0xff), __ATOMIC_RELAXED, __ATOMIC_RELAXED, __HIP_MEMORY_SCOPE_AGENT);
;                                      __hip_atomic_store(tmo, 1u, __ATOMIC_RELAXED, __HIP_MEMORY_SCOPE_AGENT); }
;                     dead = true; break; }
;                 __builtin_amdgcn_s_sleep(2);
;             }
;             __builtin_amdgcn_fence(__ATOMIC_ACQUIRE, "agent");
;             if (lane == 0) flag[0] = dead ? 1u : 0u;
;         }
.LBB0_807:
	s_waitcnt vmcnt(0)
	s_nop 0
	s_nop 0
	s_and_b64 exec, exec, s[42:43]
	v_cndmask_b32_e64 v164, 0, 1, s[2:3]
	ds_write_b32 v193, v164 offset:10240

; __device__ __forceinline__ unsigned xb_ld(unsigned* p)              { return __hip_atomic_load(p, __ATOMIC_RELAXED, __HIP_MEMORY_SCOPE_AGENT); }
; #define XB_SPIN(cond, bar) do { unsigned _sp = 0; while (cond) { __builtin_amdgcn_s_sleep(1); \
;     if ((++_sp & 255u) == 0u) { if (xb_ld(&(bar)[XB_TMO])) break; if (_sp > XB_SPIN_CAP) { atomicAdd(&(bar)[XB_TMO], 1u); break; } } } } while (0)
; __device__ __forceinline__ bool is_t0(int wave) { return wave == 0 && olane() == 0; }
; __device__ __forceinline__ void xcdl_wait_t0(const XcdBarrier& b) {
;     if (is_t0(b.wave)) {
;         unsigned* bar = b.bar; asm volatile("" : "+s"(bar));
;         const unsigned gen = b.st[5];
;         XB_SPIN(xb_ld(&bar[XB_LGEN(b.x)]) == gen, bar);
;         __builtin_amdgcn_fence(__ATOMIC_ACQUIRE, "agent");
;         asm volatile("s_waitcnt vmcnt(0)" ::: "memory");
;     }
;     __device__ __forceinline__ void gate() const {
;         if (gate_cnt) psync_wait(gate_cnt, st.tmo, 0x900u);
;         if (gate_xcc) { xcdl_wait_t0(gb); asm volatile("s_waitcnt lgkmcnt(0)" ::: "memory"); __builtin_amdgcn_s_barrier(); asm volatile("" ::: "memory"); }
;     }
.LBB0_837:
	s_or_b64 exec, exec, s[60:61]
	s_waitcnt vmcnt(0) lgkmcnt(0)
	s_nop 0
	s_nop 0
	s_waitcnt vmcnt(0)
